# speedup vs baseline: 1.0080x; 1.0080x over previous
; #define MFMA16(a, b, c) __builtin_amdgcn_mfma_f32_16x16x32_bf16(a, b, c, 0, 0, 0)
; __device__ __forceinline__ void phase_ret_u(PP p, const int g_wid, int layer) {
;     ...
;     f32x4 af[8], ab[8];
; #pragma unroll
;     for (int et = 0; et < 8; ++et) { af[et] = f32x4{0.f, 0.f, 0.f, 0.f}; ab[et] = f32x4{0.f, 0.f, 0.f, 0.f}; }
; #pragma unroll
;     for (int ks = 0; ks < 4; ++ks) {
;       bf16x8 a1 = tr_frag(Kf + (ks * 32) * 136 + wid * 16, 136, lane);
;       bf16x8 a2 = tr_frag(Kb + (ks * 32) * 136 + wid * 16, 136, lane);
; #pragma unroll
;       for (int et = 0; et < 8; ++et) {
;         bf16x8 bv = tr_frag(Vs + (ks * 32) * 136 + et * 16, 136, lane);
;         af[et] = MFMA16(a1, bv, af[et]);
;         ab[et] = MFMA16(a2, bv, ab[et]);
;       }
;     }
.LBB0_229:
	s_or_b64 exec, exec, s[6:7]
	s_waitcnt lgkmcnt(0)
	s_barrier
	ds_read_b64_tr_b16 v[2:3], v88
	ds_read_b64_tr_b16 v[4:5], v88 offset:1088
	ds_read_b64_tr_b16 v[6:7], v88 offset:34816
	ds_read_b64_tr_b16 v[8:9], v88 offset:35904
	ds_read_b64_tr_b16 v[12:13], v89 offset:1088
	ds_read_b64_tr_b16 v[10:11], v89
	ds_read_b64_tr_b16 v[14:15], v89 offset:32
	s_waitcnt lgkmcnt(1)
	v_mfma_f32_16x16x32_bf16 v[58:61], v[2:5], v[10:13], 0
	ds_read_b64_tr_b16 v[16:17], v89 offset:1120
	s_ashr_i32 s9, s8, 31
	s_lshl_b64 s[6:7], s[8:9], 16
	v_mfma_f32_16x16x32_bf16 v[62:65], v[6:9], v[10:13], 0
	ds_read_b64_tr_b16 v[10:11], v89 offset:64
	ds_read_b64_tr_b16 v[12:13], v89 offset:1152
	s_add_u32 s6, s22, s6
	s_addc_u32 s7, s23, s7
	s_waitcnt lgkmcnt(0)
	v_mfma_f32_16x16x32_bf16 v[50:53], v[2:5], v[10:13], 0
	v_mov_b32_e32 v69, v1
	v_mov_b32_e32 v75, v1
	v_mov_b32_e32 v77, v1
	v_mfma_f32_16x16x32_bf16 v[54:57], v[6:9], v[10:13], 0
	ds_read_b64_tr_b16 v[10:11], v89 offset:96
	ds_read_b64_tr_b16 v[12:13], v89 offset:1184
	v_mov_b32_e32 v79, v1
	v_mov_b32_e32 v81, v1
	s_waitcnt lgkmcnt(0)
	v_mfma_f32_16x16x32_bf16 v[42:45], v[2:5], v[10:13], 0
	v_mov_b32_e32 v83, v1
	v_mov_b32_e32 v85, v1
	v_mfma_f32_16x16x32_bf16 v[46:49], v[6:9], v[10:13], 0
	ds_read_b64_tr_b16 v[10:11], v89 offset:128
	ds_read_b64_tr_b16 v[12:13], v89 offset:1216
	v_mfma_f32_16x16x32_bf16 v[34:37], v[2:5], v[14:17], 0
	v_mfma_f32_16x16x32_bf16 v[38:41], v[6:9], v[14:17], 0
	s_waitcnt lgkmcnt(0)
	v_mfma_f32_16x16x32_bf16 v[26:29], v[2:5], v[10:13], 0
	v_mfma_f32_16x16x32_bf16 v[30:33], v[6:9], v[10:13], 0
	ds_read_b64_tr_b16 v[10:11], v89 offset:160
	ds_read_b64_tr_b16 v[12:13], v89 offset:1248
	ds_read_b64_tr_b16 v[14:15], v89 offset:192
	ds_read_b64_tr_b16 v[16:17], v89 offset:1280
	ds_read_b64_tr_b16 v[90:91], v89 offset:224
	ds_read_b64_tr_b16 v[92:93], v89 offset:1312
	s_waitcnt lgkmcnt(4)
	v_mfma_f32_16x16x32_bf16 v[18:21], v[2:5], v[10:13], 0
	v_mfma_f32_16x16x32_bf16 v[22:25], v[6:9], v[10:13], 0
	s_waitcnt lgkmcnt(2)
	v_mfma_f32_16x16x32_bf16 v[10:13], v[2:5], v[14:17], 0
	v_mfma_f32_16x16x32_bf16 v[14:17], v[6:9], v[14:17], 0
	s_waitcnt lgkmcnt(0)
	v_mfma_f32_16x16x32_bf16 v[2:5], v[2:5], v[90:93], 0
	v_mfma_f32_16x16x32_bf16 v[6:9], v[6:9], v[90:93], 0
	ds_read_b64_tr_b16 v[90:91], v88 offset:8704
	ds_read_b64_tr_b16 v[92:93], v88 offset:9792
	ds_read_b64_tr_b16 v[94:95], v88 offset:43520
	ds_read_b64_tr_b16 v[96:97], v88 offset:44608
	ds_read_b64_tr_b16 v[98:99], v89 offset:8704
	ds_read_b64_tr_b16 v[100:101], v89 offset:9792
	s_waitcnt lgkmcnt(0)
	v_mfma_f32_16x16x32_bf16 v[58:61], v[90:93], v[98:101], v[58:61]
	v_mfma_f32_16x16x32_bf16 v[62:65], v[94:97], v[98:101], v[62:65]
	ds_read_b64_tr_b16 v[98:99], v89 offset:8736
	ds_read_b64_tr_b16 v[100:101], v89 offset:9824
	s_waitcnt lgkmcnt(0)
	v_mfma_f32_16x16x32_bf16 v[34:37], v[90:93], v[98:101], v[34:37]
	v_mfma_f32_16x16x32_bf16 v[38:41], v[94:97], v[98:101], v[38:41]
	ds_read_b64_tr_b16 v[98:99], v89 offset:8768
	ds_read_b64_tr_b16 v[100:101], v89 offset:9856
	s_waitcnt lgkmcnt(0)
	v_mfma_f32_16x16x32_bf16 v[50:53], v[90:93], v[98:101], v[50:53]
	v_mfma_f32_16x16x32_bf16 v[54:57], v[94:97], v[98:101], v[54:57]
	ds_read_b64_tr_b16 v[98:99], v89 offset:8800
	ds_read_b64_tr_b16 v[100:101], v89 offset:9888
	s_waitcnt lgkmcnt(0)
	v_mfma_f32_16x16x32_bf16 v[42:45], v[90:93], v[98:101], v[42:45]
	v_mfma_f32_16x16x32_bf16 v[46:49], v[94:97], v[98:101], v[46:49]
	ds_read_b64_tr_b16 v[98:99], v89 offset:8832
	ds_read_b64_tr_b16 v[100:101], v89 offset:9920
	s_waitcnt lgkmcnt(0)
	v_mfma_f32_16x16x32_bf16 v[26:29], v[90:93], v[98:101], v[26:29]
	v_mfma_f32_16x16x32_bf16 v[30:33], v[94:97], v[98:101], v[30:33]
	ds_read_b64_tr_b16 v[98:99], v89 offset:8864
	ds_read_b64_tr_b16 v[100:101], v89 offset:9952
	s_waitcnt lgkmcnt(0)
	v_mfma_f32_16x16x32_bf16 v[18:21], v[90:93], v[98:101], v[18:21]
	v_mfma_f32_16x16x32_bf16 v[22:25], v[94:97], v[98:101], v[22:25]
	ds_read_b64_tr_b16 v[98:99], v89 offset:8896
	ds_read_b64_tr_b16 v[100:101], v89 offset:9984
	s_waitcnt lgkmcnt(0)
	v_mfma_f32_16x16x32_bf16 v[10:13], v[90:93], v[98:101], v[10:13]
	v_mfma_f32_16x16x32_bf16 v[14:17], v[94:97], v[98:101], v[14:17]
	ds_read_b64_tr_b16 v[98:99], v89 offset:8928
	ds_read_b64_tr_b16 v[100:101], v89 offset:10016
	s_waitcnt lgkmcnt(0)
	v_mfma_f32_16x16x32_bf16 v[2:5], v[90:93], v[98:101], v[2:5]
	v_mfma_f32_16x16x32_bf16 v[6:9], v[94:97], v[98:101], v[6:9]
	ds_read_b64_tr_b16 v[90:91], v88 offset:17408
	ds_read_b64_tr_b16 v[92:93], v88 offset:18496
	ds_read_b64_tr_b16 v[94:95], v88 offset:52224
	ds_read_b64_tr_b16 v[96:97], v88 offset:53312
	ds_read_b64_tr_b16 v[98:99], v89 offset:17408
	ds_read_b64_tr_b16 v[100:101], v89 offset:18496
	s_waitcnt lgkmcnt(0)
	v_mfma_f32_16x16x32_bf16 v[58:61], v[90:93], v[98:101], v[58:61]
	v_mfma_f32_16x16x32_bf16 v[62:65], v[94:97], v[98:101], v[62:65]
	ds_read_b64_tr_b16 v[98:99], v89 offset:17440
	ds_read_b64_tr_b16 v[100:101], v89 offset:18528
	s_waitcnt lgkmcnt(0)
	v_mfma_f32_16x16x32_bf16 v[34:37], v[90:93], v[98:101], v[34:37]
	v_mfma_f32_16x16x32_bf16 v[38:41], v[94:97], v[98:101], v[38:41]
	ds_read_b64_tr_b16 v[98:99], v89 offset:17472
	ds_read_b64_tr_b16 v[100:101], v89 offset:18560
	s_waitcnt lgkmcnt(0)
	v_mfma_f32_16x16x32_bf16 v[102:105], v[90:93], v[98:101], v[50:53]
	s_nop 2
	ds_read_b64_tr_b16 v[50:51], v89 offset:17504
	ds_read_b64_tr_b16 v[52:53], v89 offset:18592
	s_waitcnt lgkmcnt(0)
	v_mfma_f32_16x16x32_bf16 v[106:109], v[90:93], v[50:53], v[42:45]
	s_nop 2
	ds_read_b64_tr_b16 v[42:43], v89 offset:17536
	ds_read_b64_tr_b16 v[44:45], v89 offset:18624
	s_waitcnt lgkmcnt(0)
; #define MFMA16(a, b, c) __builtin_amdgcn_mfma_f32_16x16x32_bf16(a, b, c, 0, 0, 0)
; __device__ __forceinline__ void phase_ret_u(PP p, const int g_wid, int layer) {
;     ...
;     for (int ks = 0; ks < 4; ++ks) {
;       bf16x8 a1 = tr_frag(Kf + (ks * 32) * 136 + wid * 16, 136, lane);
;       bf16x8 a2 = tr_frag(Kb + (ks * 32) * 136 + wid * 16, 136, lane);
; #pragma unroll
;       for (int et = 0; et < 8; ++et) {
;         bf16x8 bv = tr_frag(Vs + (ks * 32) * 136 + et * 16, 136, lane);
;         af[et] = MFMA16(a1, bv, af[et]);
;         ab[et] = MFMA16(a2, bv, ab[et]);
;       }
;     }
;     u16* stf = ST + ((long)(gc * 4 + hd) * 2) * 16384;
;     u16* stb = stf + 16384;
; #pragma unroll
;     for (int et = 0; et < 8; ++et) {
;       u16x4 o1 = {f2bf(af[et][0]), f2bf(af[et][1]), f2bf(af[et][2]), f2bf(af[et][3])};
;       u16x4 o2 = {f2bf(ab[et][0]), f2bf(ab[et][1]), f2bf(ab[et][2]), f2bf(ab[et][3])};
;       *reinterpret_cast<u16x4*>(stf + (et * 16 + fr) * 128 + wid * 16 + fq * 4) = o1;
;       *reinterpret_cast<u16x4*>(stb + (et * 16 + fr) * 128 + wid * 16 + fq * 4) = o2;
	v_mfma_f32_16x16x32_bf16 v[114:117], v[94:97], v[42:45], v[30:33]
	s_nop 2
	ds_read_b64_tr_b16 v[30:31], v89 offset:17568
	ds_read_b64_tr_b16 v[32:33], v89 offset:18656
	s_waitcnt lgkmcnt(0)
	v_mfma_f32_16x16x32_bf16 v[118:121], v[94:97], v[30:33], v[22:25]
	s_nop 2
	ds_read_b64_tr_b16 v[22:23], v89 offset:17600
	ds_read_b64_tr_b16 v[24:25], v89 offset:18688
	s_waitcnt lgkmcnt(0)
	v_mfma_f32_16x16x32_bf16 v[122:125], v[90:93], v[22:25], v[10:13]
	s_nop 2
	ds_read_b64_tr_b16 v[10:11], v89 offset:17632
	ds_read_b64_tr_b16 v[12:13], v89 offset:18720
	v_mfma_f32_16x16x32_bf16 v[98:101], v[94:97], v[98:101], v[54:57]
	v_mfma_f32_16x16x32_bf16 v[110:113], v[94:97], v[50:53], v[46:49]
	v_mfma_f32_16x16x32_bf16 v[26:29], v[90:93], v[42:45], v[26:29]
	v_mfma_f32_16x16x32_bf16 v[18:21], v[90:93], v[30:33], v[18:21]
	v_mfma_f32_16x16x32_bf16 v[126:129], v[94:97], v[22:25], v[14:17]
	s_waitcnt lgkmcnt(0)
	v_mfma_f32_16x16x32_bf16 v[90:93], v[90:93], v[10:13], v[2:5]
	v_mfma_f32_16x16x32_bf16 v[6:9], v[94:97], v[10:13], v[6:9]
	ds_read_b64_tr_b16 v[94:95], v88 offset:26112
	ds_read_b64_tr_b16 v[96:97], v88 offset:27200
	ds_read_b64_tr_b16 v[130:131], v88 offset:60928
	ds_read_b64_tr_b16 v[132:133], v88 offset:62016
	ds_read_b64_tr_b16 v[2:3], v89 offset:26112
	ds_read_b64_tr_b16 v[4:5], v89 offset:27200
	s_waitcnt lgkmcnt(0)
	v_mfma_f32_16x16x32_bf16 v[134:137], v[94:97], v[2:5], v[58:61]
	v_mfma_f32_16x16x32_bf16 v[62:65], v[130:133], v[2:5], v[62:65]
	ds_read_b64_tr_b16 v[2:3], v89 offset:26144
	ds_read_b64_tr_b16 v[4:5], v89 offset:27232
	s_nop 4
	v_bfe_u32 v71, v135, 16, 1
	v_bfe_u32 v73, v134, 16, 1
	s_waitcnt lgkmcnt(0)
	v_mfma_f32_16x16x32_bf16 v[54:57], v[94:97], v[2:5], v[34:37]
	v_add3_u32 v73, v134, v73, s33
	v_add3_u32 v71, v135, v71, s33
	v_bfe_u32 v0, v137, 16, 1
	v_mfma_f32_16x16x32_bf16 v[50:53], v[130:133], v[2:5], v[38:41]
	ds_read_b64_tr_b16 v[2:3], v89 offset:26176
	ds_read_b64_tr_b16 v[4:5], v89 offset:27264
	v_add3_u32 v0, v137, v0, s33
	s_waitcnt lgkmcnt(0)
	v_mfma_f32_16x16x32_bf16 v[46:49], v[94:97], v[2:5], v[102:105]
	v_mfma_f32_16x16x32_bf16 v[42:45], v[130:133], v[2:5], v[98:101]
	ds_read_b64_tr_b16 v[2:3], v89 offset:26208
	ds_read_b64_tr_b16 v[4:5], v89 offset:27296
	s_waitcnt lgkmcnt(0)
	v_mfma_f32_16x16x32_bf16 v[38:41], v[94:97], v[2:5], v[106:109]
	v_mfma_f32_16x16x32_bf16 v[34:37], v[130:133], v[2:5], v[110:113]
	ds_read_b64_tr_b16 v[2:3], v89 offset:26240
	ds_read_b64_tr_b16 v[4:5], v89 offset:27328
	s_waitcnt lgkmcnt(0)
	v_mfma_f32_16x16x32_bf16 v[30:33], v[94:97], v[2:5], v[26:29]
	v_mfma_f32_16x16x32_bf16 v[22:25], v[130:133], v[2:5], v[114:117]
	ds_read_b64_tr_b16 v[2:3], v89 offset:26272
	ds_read_b64_tr_b16 v[4:5], v89 offset:27360
	s_waitcnt lgkmcnt(0)
	v_mfma_f32_16x16x32_bf16 v[26:29], v[94:97], v[2:5], v[18:21]
	v_mfma_f32_16x16x32_bf16 v[10:13], v[130:133], v[2:5], v[118:121]
	ds_read_b64_tr_b16 v[2:3], v89 offset:26304
	ds_read_b64_tr_b16 v[4:5], v89 offset:27392
	ds_read_b64_tr_b16 v[58:59], v89 offset:26336
	ds_read_b64_tr_b16 v[60:61], v89 offset:27424
	s_waitcnt lgkmcnt(0)
	v_mfma_f32_16x16x32_bf16 v[18:21], v[94:97], v[58:61], v[90:93]
	v_mfma_f32_16x16x32_bf16 v[6:9], v[130:133], v[58:61], v[6:9]
	v_lshl_add_u64 v[58:59], v[66:67], 1, s[6:7]
	v_lshl_add_u64 v[58:59], v[58:59], 0, v[68:69]
	s_mov_b64 s[6:7], 0x8000
	v_lshl_add_u64 v[60:61], v[58:59], 0, s[6:7]
	s_mov_b32 s6, 0x7060302
	v_bfe_u32 v69, v136, 16, 1
	v_perm_b32 v90, v71, v73, s6
	v_bfe_u32 v71, v63, 16, 1
	v_bfe_u32 v73, v62, 16, 1
	v_add3_u32 v69, v136, v69, s33
	v_add3_u32 v62, v62, v73, s33
	v_add3_u32 v71, v63, v71, s33
	v_perm_b32 v91, v0, v69, s6
	v_bfe_u32 v0, v65, 16, 1
	v_bfe_u32 v69, v64, 16, 1
	v_perm_b32 v62, v71, v62, s6
	v_mov_b32_e32 v71, v1
	v_add3_u32 v63, v64, v69, s33
	v_add3_u32 v0, v65, v0, s33
	v_lshl_add_u64 v[64:65], v[58:59], 0, v[70:71]
	v_perm_b32 v63, v0, v63, s6
	v_mov_b64_e32 v[240:241], v[64:65]
	v_mov_b64_e32 v[200:201], v[90:91]
	v_lshl_add_u64 v[64:65], v[60:61], 0, v[70:71]
	v_mov_b64_e32 v[216:217], v[62:63]
	v_bfe_u32 v0, v57, 16, 1
	v_bfe_u32 v62, v56, 16, 1
	v_bfe_u32 v63, v55, 16, 1
	v_bfe_u32 v64, v54, 16, 1
	v_add3_u32 v63, v55, v63, s33
	v_add3_u32 v55, v56, v62, s33
	v_add3_u32 v0, v57, v0, s33
	v_add3_u32 v54, v54, v64, s33
	v_perm_b32 v55, v0, v55, s6
	v_bfe_u32 v0, v53, 16, 1
	v_bfe_u32 v56, v52, 16, 1
	v_bfe_u32 v57, v51, 16, 1
	v_bfe_u32 v62, v50, 16, 1
	v_mov_b32_e32 v73, v1
	v_perm_b32 v54, v63, v54, s6
	v_add3_u32 v50, v50, v62, s33
	v_add3_u32 v57, v51, v57, s33
	v_add3_u32 v51, v52, v56, s33
	v_add3_u32 v0, v53, v0, s33
	v_lshl_add_u64 v[52:53], v[58:59], 0, v[72:73]
	v_perm_b32 v51, v0, v51, s6
	v_perm_b32 v50, v57, v50, s6
	v_mov_b64_e32 v[202:203], v[54:55]
	v_lshl_add_u64 v[52:53], v[60:61], 0, v[72:73]
	v_mov_b64_e32 v[218:219], v[50:51]
	v_bfe_u32 v0, v49, 16, 1
	v_bfe_u32 v50, v48, 16, 1
	v_bfe_u32 v51, v47, 16, 1
	v_bfe_u32 v52, v46, 16, 1
	v_add3_u32 v51, v47, v51, s33
	v_add3_u32 v47, v48, v50, s33
	v_add3_u32 v0, v49, v0, s33
	v_add3_u32 v46, v46, v52, s33
	v_perm_b32 v47, v0, v47, s6
	v_bfe_u32 v0, v45, 16, 1
	v_bfe_u32 v48, v44, 16, 1
	v_bfe_u32 v49, v43, 16, 1
	v_bfe_u32 v50, v42, 16, 1
	v_perm_b32 v46, v51, v46, s6
	v_add3_u32 v42, v42, v50, s33
	v_add3_u32 v49, v43, v49, s33
	v_add3_u32 v43, v44, v48, s33
	v_add3_u32 v0, v45, v0, s33
	v_lshl_add_u64 v[44:45], v[58:59], 0, v[74:75]
	v_perm_b32 v43, v0, v43, s6
	v_perm_b32 v42, v49, v42, s6
	v_mov_b64_e32 v[204:205], v[46:47]
	v_lshl_add_u64 v[44:45], v[60:61], 0, v[74:75]
	v_mov_b64_e32 v[220:221], v[42:43]
	v_bfe_u32 v0, v41, 16, 1
	v_bfe_u32 v42, v40, 16, 1
	v_bfe_u32 v43, v39, 16, 1
; __device__ __forceinline__ void phase_ret_u(PP p, const int g_wid, int layer) {
;     ...
; #pragma unroll
;     for (int et = 0; et < 8; ++et) {
;       u16x4 o1 = {f2bf(af[et][0]), f2bf(af[et][1]), f2bf(af[et][2]), f2bf(af[et][3])};
;       u16x4 o2 = {f2bf(ab[et][0]), f2bf(ab[et][1]), f2bf(ab[et][2]), f2bf(ab[et][3])};
;       *reinterpret_cast<u16x4*>(stf + (et * 16 + fr) * 128 + wid * 16 + fq * 4) = o1;
;       *reinterpret_cast<u16x4*>(stb + (et * 16 + fr) * 128 + wid * 16 + fq * 4) = o2;
;     }
	v_bfe_u32 v44, v38, 16, 1
	v_add3_u32 v43, v39, v43, s33
	v_add3_u32 v39, v40, v42, s33
	v_add3_u32 v0, v41, v0, s33
	v_add3_u32 v38, v38, v44, s33
	v_perm_b32 v39, v0, v39, s6
	v_bfe_u32 v0, v37, 16, 1
	v_bfe_u32 v40, v36, 16, 1
	v_bfe_u32 v41, v35, 16, 1
	v_bfe_u32 v42, v34, 16, 1
	v_perm_b32 v38, v43, v38, s6
	v_add3_u32 v34, v34, v42, s33
	v_add3_u32 v41, v35, v41, s33
	v_add3_u32 v35, v36, v40, s33
	v_add3_u32 v0, v37, v0, s33
	v_lshl_add_u64 v[36:37], v[58:59], 0, v[76:77]
	v_perm_b32 v35, v0, v35, s6
	v_perm_b32 v34, v41, v34, s6
	v_mov_b64_e32 v[206:207], v[38:39]
	v_lshl_add_u64 v[36:37], v[60:61], 0, v[76:77]
	v_mov_b64_e32 v[222:223], v[34:35]
	v_bfe_u32 v0, v33, 16, 1
	v_bfe_u32 v34, v32, 16, 1
	v_bfe_u32 v35, v31, 16, 1
	v_bfe_u32 v36, v30, 16, 1
	v_add3_u32 v35, v31, v35, s33
	v_add3_u32 v31, v32, v34, s33
	v_add3_u32 v0, v33, v0, s33
	v_add3_u32 v30, v30, v36, s33
	v_perm_b32 v31, v0, v31, s6
	v_bfe_u32 v0, v25, 16, 1
	v_bfe_u32 v32, v24, 16, 1
	v_bfe_u32 v33, v23, 16, 1
	v_bfe_u32 v34, v22, 16, 1
	v_perm_b32 v30, v35, v30, s6
	v_add3_u32 v22, v22, v34, s33
	v_add3_u32 v33, v23, v33, s33
	v_add3_u32 v23, v24, v32, s33
	v_add3_u32 v0, v25, v0, s33
	v_lshl_add_u64 v[24:25], v[58:59], 0, v[78:79]
	v_perm_b32 v23, v0, v23, s6
	v_perm_b32 v22, v33, v22, s6
	v_mov_b64_e32 v[208:209], v[30:31]
	v_lshl_add_u64 v[24:25], v[60:61], 0, v[78:79]
	v_mov_b64_e32 v[224:225], v[22:23]
	v_bfe_u32 v0, v29, 16, 1
	v_bfe_u32 v22, v28, 16, 1
	v_bfe_u32 v23, v27, 16, 1
	v_bfe_u32 v24, v26, 16, 1
	v_mfma_f32_16x16x32_bf16 v[14:17], v[94:97], v[2:5], v[122:125]
	v_add3_u32 v24, v26, v24, s33
	v_add3_u32 v25, v27, v23, s33
	v_add3_u32 v22, v28, v22, s33
	v_add3_u32 v0, v29, v0, s33
	v_perm_b32 v23, v0, v22, s6
	v_perm_b32 v22, v25, v24, s6
	v_bfe_u32 v0, v13, 16, 1
	v_bfe_u32 v24, v12, 16, 1
	v_bfe_u32 v25, v11, 16, 1
	v_bfe_u32 v26, v10, 16, 1
	v_mfma_f32_16x16x32_bf16 v[2:5], v[130:133], v[2:5], v[126:129]
	v_add3_u32 v10, v10, v26, s33
	v_add3_u32 v25, v11, v25, s33
	v_add3_u32 v11, v12, v24, s33
	v_add3_u32 v0, v13, v0, s33
	v_lshl_add_u64 v[12:13], v[58:59], 0, v[80:81]
	v_perm_b32 v11, v0, v11, s6
	v_perm_b32 v10, v25, v10, s6
	v_mov_b64_e32 v[210:211], v[22:23]
	v_lshl_add_u64 v[12:13], v[60:61], 0, v[80:81]
	v_mov_b64_e32 v[226:227], v[10:11]
	v_bfe_u32 v0, v17, 16, 1
	v_bfe_u32 v10, v16, 16, 1
	v_bfe_u32 v11, v15, 16, 1
	v_bfe_u32 v12, v14, 16, 1
	v_add3_u32 v12, v14, v12, s33
	v_add3_u32 v13, v15, v11, s33
	v_add3_u32 v10, v16, v10, s33
	v_add3_u32 v0, v17, v0, s33
	v_perm_b32 v11, v0, v10, s6
	v_perm_b32 v10, v13, v12, s6
	v_bfe_u32 v0, v5, 16, 1
	v_bfe_u32 v12, v4, 16, 1
	v_bfe_u32 v13, v3, 16, 1
	v_bfe_u32 v14, v2, 16, 1
	v_add3_u32 v2, v2, v14, s33
	v_add3_u32 v13, v3, v13, s33
	v_add3_u32 v3, v4, v12, s33
	v_add3_u32 v0, v5, v0, s33
	v_lshl_add_u64 v[4:5], v[58:59], 0, v[82:83]
	v_perm_b32 v3, v0, v3, s6
	v_perm_b32 v2, v13, v2, s6
	v_mov_b64_e32 v[212:213], v[10:11]
	v_lshl_add_u64 v[4:5], v[60:61], 0, v[82:83]
	v_mov_b64_e32 v[228:229], v[2:3]
	v_bfe_u32 v0, v21, 16, 1
	v_bfe_u32 v2, v20, 16, 1
	v_bfe_u32 v3, v19, 16, 1
	v_bfe_u32 v4, v18, 16, 1
	v_add3_u32 v4, v18, v4, s33
	v_add3_u32 v5, v19, v3, s33
	v_add3_u32 v2, v20, v2, s33
	v_add3_u32 v0, v21, v0, s33
	v_perm_b32 v3, v0, v2, s6
	v_perm_b32 v2, v5, v4, s6
	v_bfe_u32 v0, v9, 16, 1
	v_bfe_u32 v4, v8, 16, 1
	v_bfe_u32 v5, v7, 16, 1
	v_bfe_u32 v10, v6, 16, 1
	v_add3_u32 v6, v6, v10, s33
	v_add3_u32 v7, v7, v5, s33
	v_add3_u32 v4, v8, v4, s33
	v_add3_u32 v0, v9, v0, s33
	v_perm_b32 v5, v0, v4, s6
	v_perm_b32 v4, v7, v6, s6
	v_readlane_b32 s6, v254, 4
	v_lshl_add_u64 v[6:7], v[58:59], 0, v[84:85]
	s_add_i32 s8, s8, s6
	v_mov_b64_e32 v[214:215], v[2:3]
	v_lshl_add_u64 v[2:3], v[60:61], 0, v[84:85]
	v_mov_b64_e32 v[230:231], v[4:5]
	v_bfe_u32 v242, v86, 4, 1
	v_mul_u32_u24_e32 v242, 0xff8, v242
	v_mov_b32_e32 v243, 0
	v_lshl_add_u64 v[240:241], v[240:241], 0, v[242:243]
	s_nop 1
	v_permlane16_swap_b32_e32 v200, v202
	v_permlane16_swap_b32_e32 v201, v203
	v_permlane16_swap_b32_e32 v204, v206
	v_permlane16_swap_b32_e32 v205, v207
	v_permlane16_swap_b32_e32 v208, v210
	v_permlane16_swap_b32_e32 v209, v211
	v_permlane16_swap_b32_e32 v212, v214
	v_permlane16_swap_b32_e32 v213, v215
	v_permlane16_swap_b32_e32 v216, v218
	v_permlane16_swap_b32_e32 v217, v219
	v_permlane16_swap_b32_e32 v220, v222
	v_permlane16_swap_b32_e32 v221, v223
	v_permlane16_swap_b32_e32 v224, v226
	v_permlane16_swap_b32_e32 v225, v227
	v_permlane16_swap_b32_e32 v228, v230
	v_permlane16_swap_b32_e32 v229, v231
	global_store_dwordx4 v[240:241], v[200:203], off
	v_add_co_u32_e32 v240, vcc, 0x2000, v240
	s_nop 1
	v_addc_co_u32_e32 v241, vcc, 0, v241, vcc
	global_store_dwordx4 v[240:241], v[204:207], off
	v_add_co_u32_e32 v240, vcc, 0x2000, v240
	s_nop 1
	v_addc_co_u32_e32 v241, vcc, 0, v241, vcc
	global_store_dwordx4 v[240:241], v[208:211], off
	v_add_co_u32_e32 v240, vcc, 0x2000, v240
	s_nop 1
	v_addc_co_u32_e32 v241, vcc, 0, v241, vcc
	global_store_dwordx4 v[240:241], v[212:215], off
	v_add_co_u32_e32 v240, vcc, 0x2000, v240
	s_nop 1
	v_addc_co_u32_e32 v241, vcc, 0, v241, vcc
	global_store_dwordx4 v[240:241], v[216:219], off
	v_add_co_u32_e32 v240, vcc, 0x2000, v240
	s_nop 1
	v_addc_co_u32_e32 v241, vcc, 0, v241, vcc
	global_store_dwordx4 v[240:241], v[220:223], off
	v_add_co_u32_e32 v240, vcc, 0x2000, v240
	s_nop 1
	v_addc_co_u32_e32 v241, vcc, 0, v241, vcc
	global_store_dwordx4 v[240:241], v[224:227], off
	v_add_co_u32_e32 v240, vcc, 0x2000, v240
	s_nop 1
	v_addc_co_u32_e32 v241, vcc, 0, v241, vcc
	global_store_dwordx4 v[240:241], v[228:231], off
	s_cmpk_gt_i32 s8, 0x627
	s_cbranch_scc1 .LBB0_248
